# baseline (speedup 1.0000x reference)
; #define AT_PREFETCH(ckk) do { const size_t tk_ = tokb + (size_t)(ckk) * 64 + (tg >> 2); \
;         _Pragma("unroll") for (int q = 0; q < 4; ++q) { kpre[q] = *(const u32x4*)(P + tk_ * NINP + C_CK + h * 128 + (tg & 3) * 32 + q * 8); \
;             vpre[q] = *(const u32x4*)(VTBh + (size_t)(ckk) * 64 + q * 8); } } while (0)
; __device__ __forceinline__ void attn_unit(int layer, int sample, int b, int c, int hp, unsigned char* shm) {
;     ...
;     f32x4 ao[8];
; #pragma unroll
;     for (int d = 0; d < 8; ++d) ao[d] = (f32x4){0.f, 0.f, 0.f, 0.f};
;     float mrun = -1e30f, lrun = 0.f;
;     const int qpos = sample ? 4096 + m * 16 + fr : c * 64 + m * 16 + fr;
;     u32x4 kpre[4], vpre[4];
;     const bf16_t* VTBh = (const bf16_t*)(p->ws + WS_VTB) + (((size_t)b * 8 + h) * 128 + (tg >> 1)) * 2048 + (tg & 1) * 32;
;     ...
;     if (!sample) { const int ck0 = c < 8 ? 0 : c - 8; AT_PREFETCH(ck0); }
.LBB0_798:
	s_andn2_saveexec_b64 s[28:29], s[28:29]
	v_lshlrev_b32_e32 v148, 7, v12
	v_lshrrev_b32_sdwa v8, v222, v1 dst_sel:DWORD dst_unused:UNUSED_PAD src0_sel:DWORD src1_sel:BYTE_0
	v_and_b32_e32 v6, 0x60, v22
	v_ashrrev_i32_e32 v149, 31, v148
	v_mov_b32_e32 v7, v0
	s_or_b64 exec, exec, s[28:29]
	s_movk_i32 s28, 0x4400
	v_mad_i32_i24 v28, v10, s28, 0
	v_lshl_add_u32 v29, v10, 10, v28
	v_lshl_add_u32 v35, v9, 1, v29
	v_mov_b32_e32 v9, v0
	v_lshlrev_b64 v[150:151], 9, v[12:13]
	v_lshl_add_u64 v[12:13], v[16:17], 0, v[8:9]
	v_mov_b64_e32 v[24:25], s[6:7]
	v_mul_lo_u32 v26, v13, s68
	v_mad_u64_u32 v[22:23], s[28:29], v12, s68, 0
	v_mad_u64_u32 v[12:13], s[6:7], v12, s68, v[24:25]
	v_and_b32_e32 v36, 3, v1
	v_add_u32_e32 v23, v23, v26
	v_add_u32_e32 v13, v26, v13
	v_lshlrev_b64 v[26:27], 1, v[148:149]
	v_cndmask_b32_e64 v20, v31, v214, s[4:5]
	v_lshl_add_u64 v[12:13], v[12:13], 0, v[26:27]
	v_lshlrev_b32_e32 v152, 6, v36
	v_mov_b32_e32 v153, v0
	v_or3_b32 v176, v32, v34, v20
	v_lshlrev_b64 v[20:21], 9, v[14:15]
	v_lshl_add_u64 v[12:13], v[12:13], 0, v[152:153]
	s_mov_b64 s[6:7], 0x3820
	v_lshl_add_u64 v[20:21], v[20:21], 0, s[12:13]
	v_lshl_add_u64 v[154:155], v[12:13], 0, s[6:7]
	v_lshl_add_u64 v[12:13], v[18:19], 0, s[0:1]
	v_mad_i32_i24 v177, v8, s95, v28
	v_lshl_add_u64 v[20:21], v[20:21], 0, v[8:9]
	v_lshl_add_u64 v[8:9], v[12:13], 0, v[8:9]
	v_lshlrev_b64 v[156:157], 12, v[8:9]
	v_and_b32_e32 v8, 63, v1
	v_mov_b32_e32 v9, v0
	v_lshrrev_b32_e32 v18, 1, v1
	v_lshl_add_u64 v[16:17], v[16:17], 0, v[8:9]
	v_lshlrev_b32_e32 v34, 5, v36
	v_lshlrev_b32_e32 v179, 7, v36
	v_and_b32_e32 v36, 0x60, v18
	v_mad_u64_u32 v[18:19], s[28:29], v16, s68, v[24:25]
	v_mov_b32_e32 v16, v19
	v_mad_u64_u32 v[16:17], s[28:29], v17, s68, v[16:17]
	v_mov_b32_e32 v19, v16
	v_lshl_add_u64 v[16:17], v[18:19], 0, v[26:27]
	v_lshlrev_b32_e32 v18, 1, v36
	v_mov_b32_e32 v19, v0
	v_lshl_add_u64 v[16:17], v[16:17], 0, v[18:19]
	s_mov_b64 s[28:29], 0x4020
	v_lshl_add_u64 v[12:13], v[12:13], 0, v[8:9]
	v_lshl_add_u64 v[158:159], v[16:17], 0, s[28:29]
	v_lshlrev_b64 v[160:161], 12, v[12:13]
	v_mul_u32_u24_e32 v9, 0x90, v32
	v_lshlrev_b32_e32 v12, 3, v33
	s_mov_b32 s28, 0x128000
	v_add3_u32 v181, v29, v9, v12
	v_mad_u64_u32 v[12:13], s[28:29], v30, s28, v[22:23]
	v_lshl_add_u32 v178, v6, 1, v177
	v_lshl_add_u64 v[6:7], v[6:7], 1, v[12:13]
	v_lshl_add_u64 v[6:7], v[6:7], 0, v[26:27]
	v_lshl_add_u64 v[6:7], s[20:21], 0, v[6:7]
	s_mov_b64 s[28:29], 0xd60b840
	v_lshl_add_u64 v[162:163], v[6:7], 0, s[28:29]
	v_and_b32_e32 v6, 3, v11
	v_mul_u32_u24_e32 v37, 0x90, v4
	v_lshl_add_u64 v[2:3], v[4:5], 0, v[2:3]
	v_lshlrev_b32_e32 v4, 8, v6
	v_mov_b32_e32 v5, v0
	v_ashrrev_i32_e32 v11, 31, v10
	v_lshl_add_u64 v[2:3], v[2:3], 0, v[4:5]
	v_lshlrev_b64 v[4:5], 7, v[10:11]
	v_lshl_add_u64 v[2:3], v[2:3], 0, v[4:5]
	v_and_b32_e32 v5, 1, v1
	v_lshlrev_b64 v[2:3], 12, v[2:3]
	v_lshlrev_b32_e32 v4, 7, v30
	v_lshlrev_b32_e32 v5, 6, v5
	v_or3_b32 v2, v2, v4, v5
	v_lshl_add_u64 v[2:3], s[20:21], 0, v[2:3]
	s_mov_b64 s[28:29], 0x33627ca0
	v_lshl_add_u64 v[164:165], v[2:3], 0, s[28:29]
	v_lshlrev_b64 v[2:3], 21, v[14:15]
	v_lshl_add_u64 v[2:3], s[16:17], 0, v[2:3]
	v_lshlrev_b32_e32 v4, 12, v8
	v_mov_b32_e32 v5, v0
	v_lshl_add_u64 v[2:3], v[2:3], 0, v[4:5]
	v_lshlrev_b32_e32 v4, 10, v6
	v_lshl_add_u64 v[2:3], v[2:3], 0, v[4:5]
	v_lshlrev_b64 v[6:7], 9, v[10:11]
	v_lshlrev_b32_e32 v1, 1, v1
	v_cmp_gt_u32_e64 s[6:7], 32, v8
	v_lshl_add_u32 v38, v8, 1, v29
	v_lshl_add_u64 v[2:3], v[2:3], 0, v[6:7]
	v_and_b32_e32 v8, 0x180, v1
	v_mov_b32_e32 v9, v0
	v_lshl_add_u64 v[166:167], v[2:3], 0, v[8:9]
	v_lshlrev_b64 v[2:3], 12, v[20:21]
	v_or_b32_e32 v2, v2, v4
	v_lshl_add_u32 v39, v33, 4, v28
	v_add_u32_e32 v185, -8, v30
	v_sub_u32_e32 v186, 0, v31
	v_lshl_add_u64 v[168:169], v[2:3], 0, v[6:7]
	v_mov_b32_e32 v2, v0
	v_mov_b32_e32 v3, v0
	v_mov_b32_e32 v4, v0
	v_mov_b32_e32 v6, v0
	v_mov_b32_e32 v7, v0
	v_mov_b32_e32 v8, v0
	v_mov_b32_e32 v10, v0
	v_mov_b32_e32 v11, v0
	v_mov_b32_e32 v12, v0
	v_mov_b32_e32 v13, v0
	v_mov_b32_e32 v14, v0
	v_mov_b32_e32 v15, v0
	v_mov_b32_e32 v16, v0
	v_mov_b32_e32 v17, v0
	v_mov_b32_e32 v18, v0
	v_mov_b32_e32 v20, v0
	v_mov_b32_e32 v21, v0
	v_mov_b32_e32 v22, v0
	v_mov_b32_e32 v23, v0
	v_mov_b32_e32 v24, v0
	v_mov_b32_e32 v25, v0
	v_mov_b32_e32 v26, v0
	v_mov_b32_e32 v27, v0
	v_mov_b32_e32 v28, v0
	v_mov_b32_e32 v29, v0
	v_mov_b32_e32 v30, v0
	v_mov_b32_e32 v31, v0
	v_mov_b32_e32 v142, v0
	v_mov_b32_e32 v143, v0
	v_lshlrev_b32_e32 v153, 2, v33
	v_mul_u32_u24_e32 v40, 0x90, v36
	v_mul_u32_u24_e32 v41, 0x110, v32
	v_mov_b32_e32 v1, v0
	v_mov_b32_e32 v144, v0
	v_mov_b32_e32 v145, v0
	v_mov_b64_e32 v[138:139], v[142:143]
	v_mov_b64_e32 v[134:135], v[142:143]
	v_mov_b64_e32 v[130:131], v[142:143]
	v_mov_b64_e32 v[126:127], v[142:143]
	v_mov_b64_e32 v[122:123], v[142:143]
	v_mov_b64_e32 v[118:119], v[142:143]
	v_mov_b64_e32 v[114:115], v[142:143]
	v_mov_b64_e32 v[32:33], v[30:31]
	v_not_b32_e32 v180, v153
	v_add_u32_e32 v182, 0x900, v181
	v_add_u32_e32 v183, 0x1200, v181
	v_add_u32_e32 v184, 0x1b00, v181
	s_mov_b32 s33, 0
	v_or_b32_e32 v168, v168, v179
	v_mov_b32_e32 v187, 0
	v_mov_b32_e32 v191, 0xf149f2ca
	s_movk_i32 s35, 0xf200
	s_mov_b64 s[28:29], 0
	v_add_u32_e32 v188, v35, v37
	v_lshlrev_b32_e32 v170, 2, v34
	v_lshlrev_b32_e32 v172, 2, v36
	v_add_u32_e32 v189, v38, v40
	v_add_u32_e32 v190, v39, v41
	v_mov_b64_e32 v[140:141], v[144:145]
	v_mov_b64_e32 v[136:137], v[144:145]
	v_mov_b64_e32 v[132:133], v[144:145]
	v_mov_b64_e32 v[128:129], v[144:145]
	v_mov_b64_e32 v[124:125], v[144:145]
	v_mov_b64_e32 v[120:121], v[144:145]
	v_mov_b64_e32 v[116:117], v[144:145]
	v_mov_b64_e32 v[30:31], v[28:29]
	v_mov_b64_e32 v[28:29], v[26:27]
	v_mov_b64_e32 v[26:27], v[24:25]
	v_mov_b64_e32 v[24:25], v[22:23]
	v_mov_b64_e32 v[22:23], v[20:21]
	v_mov_b64_e32 v[20:21], v[18:19]
	v_mov_b64_e32 v[18:19], v[16:17]
	v_mov_b64_e32 v[16:17], v[14:15]
	v_mov_b64_e32 v[14:15], v[12:13]
	v_mov_b64_e32 v[12:13], v[10:11]
	v_mov_b64_e32 v[10:11], v[8:9]
	v_mov_b64_e32 v[8:9], v[6:7]
	v_mov_b64_e32 v[6:7], v[4:5]
	v_mov_b64_e32 v[4:5], v[2:3]
	v_mov_b64_e32 v[2:3], v[0:1]
	s_cmp_lg_u64 s[8:9], 0
	s_cselect_b32 s98, 0x13000, 0
	s_branch .LBB0_804

; __device__ __forceinline__ void attn_unit(int layer, int sample, int b, int c, int hp, unsigned char* shm) {
;     ...
;     for (int kt = 0; kt < 9; ++kt) {
;         const int ck = c - 8 + kt;
;         if (!sample && ck < 0) continue;
;         __syncthreads();
;         if (!sample) {
; #pragma unroll
;             for (int q = 0; q < 4; ++q) { *(u32x4*)(Kt + (tg >> 2) * 136 + (tg & 3) * 32 + q * 8) = kpre[q]; *(u32x4*)(VT + (tg >> 1) * 72 + (tg & 1) * 32 + q * 8) = vpre[q]; }
.LBB0_803:
	s_or_b64 exec, exec, s[30:31]
	v_add_u32_e32 v178, s98, v178
	v_add_u32_e32 v188, s98, v188
	v_add_u32_e32 v190, s98, v190
	v_add_u32_e32 v181, s98, v181
	v_add_u32_e32 v182, s98, v182
	v_add_u32_e32 v183, s98, v183
	v_add_u32_e32 v184, s98, v184
	s_sub_i32 s98, 0, s98
	s_add_i32 s33, s33, 1
	s_sub_i32 s35, s35, 64
	s_add_u32 s28, s28, 0x40000
	s_mov_b64 s[30:31], 0x128000
	s_addc_u32 s29, s29, 0
	v_lshl_add_u64 v[162:163], v[162:163], 0, s[30:31]
	s_cmp_eq_u32 s28, 0x240000
	v_lshl_add_u64 v[164:165], v[164:165], 0, s[44:45]
	s_cbranch_scc1 .LBB0_832
.LBB0_804:
	v_add_u32_e32 v1, s33, v185
	v_cmp_lt_i32_e32 vcc, -1, v1
	s_or_b64 s[36:37], s[4:5], vcc
	s_and_saveexec_b64 s[30:31], s[36:37]
	s_cbranch_execz .LBB0_803
	s_cmp_lg_u32 s98, 0
	s_cbranch_scc1 .Lat_nobar
	s_waitcnt lgkmcnt(0)
	s_barrier
.Lat_nobar:
	s_and_saveexec_b64 s[36:37], s[8:9]
	s_xor_b64 s[36:37], exec, s[36:37]
	s_cbranch_execz .LBB0_807
	s_waitcnt vmcnt(4)
	ds_write_b128 v178, v[90:93]
	s_waitcnt vmcnt(0)
	ds_write_b128 v188, v[106:109] offset:34816
	ds_write_b128 v178, v[86:89] offset:16
	s_waitcnt vmcnt(0)
	ds_write_b128 v188, v[110:113] offset:34832
	ds_write_b128 v178, v[82:85] offset:32
	ds_write_b128 v188, v[102:105] offset:34848
	ds_write_b128 v178, v[94:97] offset:48
	ds_write_b128 v188, v[98:101] offset:34864
